# scan: both a^TC loads issued before the first accumulator dump (latency hidden), no VMEM wait in the second direction
# speedup vs baseline: 1.0070x; 1.0000x over previous
; #define LAS __attribute__((address_space(3)))
;     __device__ __forceinline__ void fused(const f32x4 (&acc)[2][2][4][2], const pg8::Unit& u, int wr, int wc, int fr, int fq, LAS unsigned char* lds, int wid, int lane) const {
;     ...
;                 for (int m = 0; m < 4; ++m) { LAS float* tp = T + (ai * 128 + wr * 64 + m * 16 + fr) * TP + wc * 32 + fq * 8;
;                     *(LAS f32x4*)tp = acc[ai][bj][m][0]; *(LAS f32x4*)(tp + 4) = acc[ai][bj][m][1]; }
;             asm volatile("s_waitcnt lgkmcnt(0)" ::: "memory"); __builtin_amdgcn_s_barrier(); asm volatile("" ::: "memory");
;             if (wid == 0) {
;                 const int p = lane, d = bj;
;                 const f32x2 a = AT[((l * NG + g) * 2 + d) * NP + p];
.LBB0_244:
	v_and_b32_e32 v130, 63, v1
	s_lshl_b32 s0, s46, 7
	v_lshlrev_b32_e32 v1, 1, v1
	s_add_i32 s4, s0, 0
	v_and_b32_e32 v1, 0x60, v1
	v_mul_lo_u32 v131, v142, s54
	v_add3_u32 v131, s4, v1, v131
	v_or_b32_e32 v236, s75, v130
	v_readlane_b32 s4, v252, 34
	v_readlane_b32 s5, v252, 35
	v_ashrrev_i32_e32 v237, 31, v236
	s_nop 0
	v_lshl_add_u64 v[236:237], v[236:237], 3, s[4:5]
	global_load_dwordx2 v[238:239], v[236:237], off
	global_load_dwordx2 v[240:241], v[236:237], off offset:512
	s_waitcnt vmcnt(2)
	s_barrier
	ds_write_b128 v131, v[126:129]
	ds_write_b128 v131, v[122:125] offset:16
	ds_write_b128 v131, v[118:121] offset:8448
	ds_write_b128 v131, v[114:117] offset:8464
	ds_write_b128 v131, v[110:113] offset:16896
	ds_write_b128 v131, v[106:109] offset:16912
	ds_write_b128 v131, v[102:105] offset:25344
	ds_write_b128 v131, v[98:101] offset:25360
	v_add_u32_e32 v98, 0x10800, v131
	ds_write_b128 v98, v[94:97]
	v_add_u32_e32 v94, 0x10810, v131
	ds_write_b128 v94, v[90:93]
	v_add_u32_e32 v93, 0x12900, v131
	v_add_u32_e32 v95, 0x12910, v131
	v_add_u32_e32 v96, 0x14a00, v131
	v_add_u32_e32 v97, 0x14a10, v131
	v_add_u32_e32 v99, 0x16b00, v131
	v_add_u32_e32 v100, 0x16b10, v131
	ds_write_b128 v93, v[86:89]
	ds_write_b128 v95, v[82:85]
	ds_write_b128 v96, v[78:81]
	ds_write_b128 v97, v[74:77]
	ds_write_b128 v99, v[70:73]
	ds_write_b128 v100, v[66:69]
	s_waitcnt lgkmcnt(0)
	s_barrier
	s_cmp_lt_u32 s10, 64
	v_or_b32_e32 v82, s75, v130
	s_cselect_b64 s[0:1], -1, 0
	s_cmp_gt_u32 s10, 63
	v_ashrrev_i32_e32 v83, 31, v82
	v_lshrrev_b32_e32 v71, 6, v244
	s_waitcnt vmcnt(0)
	v_mov_b32_e32 v66, v238
	v_mov_b32_e32 v67, v239
	v_mul_u32_u24_e32 v72, 0x4200, v71
	v_lshl_add_u32 v70, v130, 2, v72
	v_lshl_add_u32 v84, v71, 9, 0
	v_lshl_add_u32 v84, v130, 2, v84
	v_add_u32_e32 v84, 0x21000, v84
	v_mov_b32_e32 v80, v70
	v_mov_b32_e32 v68, 0
	v_mov_b32_e32 v69, 0
	s_mov_b32 s4, 4

; __device__ __forceinline__ unsigned cvt_pk_bf16(float lo, float hi) { unsigned r; asm volatile("v_cvt_pk_bf16_f32 %0, %1, %2" : "=v"(r) : "v"(lo), "v"(hi)); return r; }
; #define LAS __attribute__((address_space(3)))
;     __device__ __forceinline__ void fused(const f32x4 (&acc)[2][2][4][2], const pg8::Unit& u, int wr, int wc, int fr, int fq, LAS unsigned char* lds, int wid, int lane) const {
;     ...
;                 for (int m = 0; m < 4; ++m) { LAS float* tp = T + (ai * 128 + wr * 64 + m * 16 + fr) * TP + wc * 32 + fq * 8;
;                     *(LAS f32x4*)tp = acc[ai][bj][m][0]; *(LAS f32x4*)(tp + 4) = acc[ai][bj][m][1]; }
;             asm volatile("s_waitcnt lgkmcnt(0)" ::: "memory"); __builtin_amdgcn_s_barrier(); asm volatile("" ::: "memory");
;             if (wid == 0) {
;                 const int p = lane, d = bj;
;                 const f32x2 a = AT[((l * NG + g) * 2 + d) * NP + p];
;     ...
;             {
;                 const int tid = wid * 64 + lane;
; #pragma unroll
;                 for (int q = 0; q < 8; ++q) { const int e = q * 512 + tid, c = e >> 4, k8 = (e & 15) * 8;
;                     const f32x4 v0 = *(const LAS f32x4*)(T + c * TP + k8), v1 = *(const LAS f32x4*)(T + c * TP + k8 + 4);
;                     v4u w; w.x = cvt_pk_bf16(v0[0], v0[1]); w.y = cvt_pk_bf16(v0[2], v0[3]); w.z = cvt_pk_bf16(v1[0], v1[1]); w.w = cvt_pk_bf16(v1[2], v1[3]);
;                     *(v4u*)(A2 + (row0 + c) * K2 + 512 + bj * 128 + k8) = w; }
;             }
;             asm volatile("s_waitcnt vmcnt(0) lgkmcnt(0)" ::: "memory"); __builtin_amdgcn_s_barrier(); asm volatile("" ::: "memory");
.Lscan_end_f:
.LBB0_247:
	s_andn2_b32 s10, s10, 63
	v_or_b32_e32 v92, s10, v130
	v_lshlrev_b32_e32 v1, 3, v130
	v_and_b32_e32 v84, 0x78, v1
	v_ashrrev_i32_e32 v78, 4, v92
	v_lshl_add_u32 v101, v84, 2, 0
	v_mul_lo_u32 v1, v78, s54
	s_waitcnt lgkmcnt(0)
	s_barrier
	v_add_u32_e32 v1, v101, v1
	ds_read_b128 v[66:69], v1
	ds_read_b128 v[70:73], v1 offset:16
	v_readlane_b32 s4, v253, 19
	v_ashrrev_i32_e32 v79, 31, v78
	v_readlane_b32 s5, v253, 20
	s_waitcnt lgkmcnt(0)
	v_cvt_pk_bf16_f32 v74, v66, v67
	v_lshl_add_u64 v[66:67], s[38:39], 0, v[78:79]
	v_cvt_pk_bf16_f32 v75, v68, v69
	v_lshlrev_b32_e32 v84, 1, v84
	v_mov_b64_e32 v[80:81], s[4:5]
	v_mad_u64_u32 v[68:69], s[4:5], v66, s89, v[80:81]
	v_mad_i32_i24 v69, v67, s89, v69
	v_mov_b32_e32 v85, v0
	v_lshl_add_u64 v[66:67], v[68:69], 0, v[84:85]
	v_add_u32_e32 v68, 0x200, v92
	v_ashrrev_i32_e32 v88, 4, v68
	v_mul_lo_u32 v68, v88, s54
	v_cvt_pk_bf16_f32 v76, v70, v71
	v_cvt_pk_bf16_f32 v77, v72, v73
	global_store_dwordx4 v[66:67], v[74:77], off offset:1024
	v_add_u32_e32 v86, v101, v68
	ds_read_b128 v[68:71], v86
	ds_read_b128 v[72:75], v86 offset:16
	v_ashrrev_i32_e32 v89, 31, v88
	s_waitcnt lgkmcnt(0)
	v_cvt_pk_bf16_f32 v76, v68, v69
	v_lshl_add_u64 v[68:69], s[38:39], 0, v[88:89]
	v_cvt_pk_bf16_f32 v77, v70, v71
	v_mad_u64_u32 v[70:71], s[4:5], v68, s89, v[80:81]
	v_mad_i32_i24 v71, v69, s89, v71
	v_cvt_pk_bf16_f32 v78, v72, v73
	v_lshl_add_u64 v[68:69], v[70:71], 0, v[84:85]
	v_add_u32_e32 v70, 0x400, v92
	v_cvt_pk_bf16_f32 v79, v74, v75
	global_store_dwordx4 v[68:69], v[76:79], off offset:1024
	s_andn2_b64 vcc, exec, s[0:1]
	s_nop 0
	v_ashrrev_i32_e32 v78, 4, v70
	v_mul_lo_u32 v70, v78, s54
	v_add_u32_e32 v87, v101, v70
	ds_read_b128 v[70:73], v87
	ds_read_b128 v[74:77], v87 offset:16
	v_ashrrev_i32_e32 v79, 31, v78
	s_waitcnt lgkmcnt(0)
	v_cvt_pk_bf16_f32 v88, v70, v71
	v_lshl_add_u64 v[70:71], s[38:39], 0, v[78:79]
	v_cvt_pk_bf16_f32 v89, v72, v73
	v_mad_u64_u32 v[72:73], s[4:5], v70, s89, v[80:81]
	v_mad_i32_i24 v73, v71, s89, v73
	v_cvt_pk_bf16_f32 v90, v74, v75
	v_lshl_add_u64 v[70:71], v[72:73], 0, v[84:85]
	v_add_u32_e32 v72, 0x600, v92
	v_cvt_pk_bf16_f32 v91, v76, v77
	global_store_dwordx4 v[70:71], v[88:91], off offset:1024
	s_nop 1
	v_ashrrev_i32_e32 v90, 4, v72
	v_mul_lo_u32 v72, v90, s54
	v_add_u32_e32 v88, v101, v72
	ds_read_b128 v[72:75], v88
	ds_read_b128 v[76:79], v88 offset:16
	v_ashrrev_i32_e32 v91, 31, v90
	s_waitcnt lgkmcnt(0)
	v_cvt_pk_bf16_f32 v102, v72, v73
	v_lshl_add_u64 v[72:73], s[38:39], 0, v[90:91]
	v_cvt_pk_bf16_f32 v103, v74, v75
	v_mad_u64_u32 v[74:75], s[4:5], v72, s89, v[80:81]
	v_mad_i32_i24 v75, v73, s89, v75
	v_lshl_add_u64 v[72:73], v[74:75], 0, v[84:85]
	v_add_u32_e32 v74, 0x800, v92
	v_cvt_pk_bf16_f32 v104, v76, v77
	v_cvt_pk_bf16_f32 v105, v78, v79
	v_ashrrev_i32_e32 v78, 4, v74
	v_mul_lo_u32 v74, v78, s54
	global_store_dwordx4 v[72:73], v[102:105], off offset:1024
	v_add_u32_e32 v89, v101, v74
	ds_read_b128 v[74:77], v89
	ds_read_b128 v[102:105], v89 offset:16
	v_ashrrev_i32_e32 v79, 31, v78
	s_waitcnt lgkmcnt(0)
	v_cvt_pk_bf16_f32 v106, v74, v75
	v_lshl_add_u64 v[74:75], s[38:39], 0, v[78:79]
	v_cvt_pk_bf16_f32 v107, v76, v77
	v_mad_u64_u32 v[76:77], s[4:5], v74, s89, v[80:81]
	v_mad_i32_i24 v77, v75, s89, v77
	v_lshl_add_u64 v[74:75], v[76:77], 0, v[84:85]
	v_add_u32_e32 v76, 0xa00, v92
	v_ashrrev_i32_e32 v110, 4, v76
	v_mul_lo_u32 v76, v110, s54
	v_cvt_pk_bf16_f32 v108, v102, v103
	v_cvt_pk_bf16_f32 v109, v104, v105
	global_store_dwordx4 v[74:75], v[106:109], off offset:1024
	v_add_u32_e32 v90, v101, v76
	ds_read_b128 v[76:79], v90
	ds_read_b128 v[102:105], v90 offset:16
	v_ashrrev_i32_e32 v111, 31, v110
	s_waitcnt lgkmcnt(0)
	v_cvt_pk_bf16_f32 v106, v76, v77
	v_lshl_add_u64 v[76:77], s[38:39], 0, v[110:111]
	v_cvt_pk_bf16_f32 v107, v78, v79
	v_mad_u64_u32 v[78:79], s[4:5], v76, s89, v[80:81]
	v_mad_i32_i24 v79, v77, s89, v79
	v_lshl_add_u64 v[76:77], v[78:79], 0, v[84:85]
	v_add_u32_e32 v78, 0xc00, v92
	v_ashrrev_i32_e32 v78, 4, v78
	v_mul_lo_u32 v79, v78, s54
	v_cvt_pk_bf16_f32 v108, v102, v103
	v_cvt_pk_bf16_f32 v109, v104, v105
	global_store_dwordx4 v[76:77], v[106:109], off offset:1024
	v_add_u32_e32 v91, v101, v79
	ds_read_b128 v[102:105], v91
	ds_read_b128 v[106:109], v91 offset:16
	v_ashrrev_i32_e32 v79, 31, v78
	v_lshl_add_u64 v[78:79], s[38:39], 0, v[78:79]
	s_waitcnt lgkmcnt(0)
	v_cvt_pk_bf16_f32 v102, v102, v103
	v_cvt_pk_bf16_f32 v103, v104, v105
	v_cvt_pk_bf16_f32 v104, v106, v107
	v_mad_u64_u32 v[106:107], s[4:5], v78, s89, v[80:81]
	v_add_u32_e32 v92, 0xe00, v92
	v_mad_i32_i24 v107, v79, s89, v107
	v_ashrrev_i32_e32 v110, 4, v92
	v_lshl_add_u64 v[78:79], v[106:107], 0, v[84:85]
	v_mul_lo_u32 v92, v110, s54
	v_cvt_pk_bf16_f32 v105, v108, v109
	global_store_dwordx4 v[78:79], v[102:105], off offset:1024
	v_add_u32_e32 v92, v101, v92
	ds_read_b128 v[102:105], v92
	ds_read_b128 v[106:109], v92 offset:16
	v_ashrrev_i32_e32 v111, 31, v110
	s_waitcnt lgkmcnt(0)
	v_cvt_pk_bf16_f32 v102, v102, v103
	v_cvt_pk_bf16_f32 v103, v104, v105
	v_cvt_pk_bf16_f32 v104, v106, v107
	v_lshl_add_u64 v[106:107], s[38:39], 0, v[110:111]
	v_mad_u64_u32 v[80:81], s[4:5], v106, s89, v[80:81]
	v_mad_i32_i24 v81, v107, s89, v81
	v_lshl_add_u64 v[80:81], v[80:81], 0, v[84:85]
	v_cvt_pk_bf16_f32 v105, v108, v109
	global_store_dwordx4 v[80:81], v[102:105], off offset:1024
	s_waitcnt vmcnt(0) lgkmcnt(0)
	s_barrier
	ds_write_b128 v131, v[62:65]
	ds_write_b128 v131, v[58:61] offset:16
	ds_write_b128 v131, v[54:57] offset:8448
	ds_write_b128 v131, v[50:53] offset:8464
	ds_write_b128 v131, v[46:49] offset:16896
	ds_write_b128 v131, v[42:45] offset:16912
	ds_write_b128 v131, v[38:41] offset:25344
	ds_write_b128 v131, v[34:37] offset:25360
	ds_write_b128 v98, v[30:33]
	ds_write_b128 v94, v[26:29]
	ds_write_b128 v93, v[22:25]
	ds_write_b128 v95, v[18:21]
	ds_write_b128 v96, v[14:17]
	ds_write_b128 v97, v[10:13]
	ds_write_b128 v99, v[6:9]
	ds_write_b128 v100, v[2:5]
	s_waitcnt lgkmcnt(0)
	s_barrier
	v_lshrrev_b32_e32 v7, 6, v244
	v_mov_b32_e32 v2, v240
	v_mov_b32_e32 v3, v241
	v_mul_u32_u24_e32 v8, 0x4200, v7
	v_lshlrev_b32_e32 v9, 2, v130
	v_sub_u32_e32 v6, v9, v8
	v_add_u32_e32 v6, 0x1ff80, v6
	v_lshl_add_u32 v18, v7, 9, 0
	v_lshl_add_u32 v18, v130, 2, v18
	v_add_u32_e32 v18, 0x21000, v18
	v_mov_b32_e32 v16, v6
	v_mov_b32_e32 v4, 0
	v_mov_b32_e32 v5, 0
	s_mov_b32 s0, 4
